# DA tile loop: back-edge rotation - pointer advance/wrap fix-up/counter moved above the per-tile s_barrier
# speedup vs baseline: 1.0056x; 1.0000x over previous
; #define SBAR() __builtin_amdgcn_sched_barrier(0)
; __device__ __forceinline__ int crow(int r, int hi) { return (r & 3) + 8 * (r >> 2) + 4 * hi; }
; #define WAIT_BAR_0() asm volatile("s_waitcnt vmcnt(0) lgkmcnt(0)\n\ts_barrier" ::: "memory")
; #define WAIT_BAR_0() asm volatile("s_waitcnt vmcnt(0) lgkmcnt(0)\n\ts_barrier" ::: "memory")
; #define WAIT_BAR_0() asm volatile("s_waitcnt vmcnt(0) lgkmcnt(0)\n\ts_barrier" ::: "memory")
; __device__ __forceinline__ void attn_unit_da(const AttnUnit& U, char* lds) {
;     ...
;   for (int j = 0; j < NT; ++j) {
;     const int st = j & 1;
;     if (j + 1 < NT) DMA_TILE(j + 1, st ^ 1);
;     float rc;
;     { const int c_ = __builtin_amdgcn_readfirstlane(cls[j]); const float* ak_ = aux + j * KVBLK;
;       if (c_ < 2) { rc = (c_ == 0) ? pq * U.nsl : -pq * U.nsl;
; #pragma unroll
;         for (int g = 0; g < 4; ++g) { const f32x4 a_ = *(const f32x4*)(ak_ + 8 * g + 4 * hi), b_ = *(const f32x4*)(ak_ + 32 + 8 * g + 4 * hi);
; #pragma unroll
;           for (int e = 0; e < 4; ++e) { p0[4 * g + e] = a_[e]; p1[4 * g + e] = b_[e]; } } }
;       else { rc = 0.f; const int* pg_ = U.posg + j * KVBLK;
; #pragma unroll
;         for (int g = 0; g < 4; ++g)
; #pragma unroll
;           for (int e = 0; e < 4; ++e) { p0[4 * g + e] = fabsf(pq - (float)(pg_[8 * g + 4 * hi + e] - pq0i)) * U.nsl; p1[4 * g + e] = fabsf(pq - (float)(pg_[32 + 8 * g + 4 * hi + e] - pq0i)) * U.nsl; } } }
;     SBAR(); qkt_acc<DQK>(p0, p1, K_lds + st * SHM_K, qr, r32, hi); SBAR();
;     const float pmax = rowmax32(p0, p1) + rc;
;     if (!__all((pmax - m_reg) * U.C < -150.f)) {
;       partialSM_rc(p0, p1, m_reg, mn, al, U.C, U.thr, rc, pmax);
;       if (__any(al < 1.f)) { if (hi == 0) al_l[r32] = al; asm volatile("s_waitcnt lgkmcnt(0)" ::: "memory");
; #pragma unroll
;         for (int d = 0; d < 8; ++d)
; #pragma unroll
;           for (int r = 0; r < 16; ++r) o[d][r] *= al_l[crow(r, hi)]; }
;       finishSM(p0, p1, al, l_reg, pa0, pa1, pa2, pa3); SBAR();
;       pv_d0_lean(o, vb0 + st * SHM_V2, pa0, pa1, pa2, pa3); SBAR();
;       pv_d0_lean(o + 4, vb0 + st * SHM_V2 + 16384, pa0, pa1, pa2, pa3);
;     }
;     WAIT_BAR_0();
;   }
.Lda_nowrap1:
	s_add_u32 s0, s0, 0xc0000
	s_addc_u32 s1, s1, 0
	s_cmpk_lg_i32 s6, 0x3f00
	s_cbranch_scc1 .Lda_nowrap2
	s_sub_u32 s0, s0, 0x3000000
	s_subb_u32 s1, s1, 0
.Lda_nowrap2:
	s_add_i32 s36, s36, 1
	s_cmpk_eq_i32 s36, 64
	s_waitcnt vmcnt(0) lgkmcnt(0)
	s_barrier
	s_cbranch_scc1 .LBB0_1948
